# prologue overlap: 6144 items per recurrence phase on the streamer WGs plus 1728 items per layer on the 18 workgroups that have one input-projection unit fewer (idle for one unit time at the end of P1)
# baseline (speedup 1.0000x reference)
; #define LAS __attribute__((address_space(3)))
; __global__ void __launch_bounds__(NTHR, 2) mega(const Args a) {
;     extern __shared__ __attribute__((aligned(16))) unsigned char lds_raw[];
;     LAS unsigned char* lds = (LAS unsigned char*)lds_raw;
;     const int wg0 = blockIdx.x, nwg0 = gridDim.x, tid = threadIdx.x;
;     for (int u = tid; u < (LDS_BYTES - LDSCTL_OFF) / 4; u += NTHR) ((LAS unsigned*)(lds + LDSCTL_OFF))[u] = 0u;
;     __syncthreads();
;     if (tid == 0) { const unsigned long long* src = (const unsigned long long*)&a.p;
; #pragma unroll
;         for (int i = 0; i < 25; ++i) *(LAS unsigned long long*)(lds + LDS_P_OFF + 8 * i) = src[i]; }
;     __syncthreads();
_Z4mega4Args:
	v_mov_b32_e32 v250, 0
	s_mov_b32 s3, 0x1b6c0
	v_writelane_b32 v250, s3, 2
	s_mov_b32 s3, 0x1b6bf
	v_writelane_b32 v250, s3, 3
	s_add_u32 s4, s0, 0xd0
	s_addc_u32 s5, s1, 0
	s_movk_i32 s3, 0x200
	v_writelane_b32 v249, s4, 0
	v_cmp_gt_u32_e32 vcc, s3, v0
	s_nop 0
	v_writelane_b32 v249, s5, 1
	s_and_saveexec_b64 s[6:7], vcc
	v_lshl_add_u32 v1, v0, 2, 0
	v_add_u32_e32 v1, 0x23800, v1
	v_mov_b32_e32 v2, 0
	ds_write_b32 v1, v2
	s_or_b64 exec, exec, s[6:7]
	s_waitcnt lgkmcnt(0)
	s_barrier
	v_cmp_eq_u32_e64 s[4:5], 0, v0
	s_mov_b64 s[22:23], exec
	s_nop 0
	v_writelane_b32 v249, s4, 2
	s_nop 1
	v_writelane_b32 v249, s5, 3
	s_and_b64 s[4:5], s[22:23], s[4:5]
	s_mov_b64 exec, s[4:5]
	s_cbranch_execz .LBB0_4
	s_load_dwordx16 s[4:19], s[0:1], 0x0
	s_add_i32 s20, 0, 0x23900
	s_load_dwordx16 s[48:63], s[0:1], 0x40
	v_mov_b32_e32 v1, s20
	s_add_i32 s20, 0, 0x23970
	s_waitcnt lgkmcnt(0)
	v_mov_b32_e32 v2, s4
	v_mov_b32_e32 v3, s5
	v_mov_b32_e32 v4, s6
	v_mov_b32_e32 v5, s7
	s_add_i32 s4, 0, 0x23910
	ds_write_b128 v1, v[2:5]
	v_mov_b32_e32 v2, s8
	v_mov_b32_e32 v3, s9
	v_mov_b32_e32 v4, s10
	v_mov_b32_e32 v5, s11
	v_mov_b32_e32 v1, s4
	s_add_i32 s4, 0, 0x23920
	ds_write_b128 v1, v[2:5]
	v_mov_b32_e32 v2, s12
	v_mov_b32_e32 v3, s13
	v_mov_b32_e32 v4, s14
	v_mov_b32_e32 v5, s15
	v_mov_b32_e32 v1, s4
	s_add_i32 s4, 0, 0x23930
	ds_write_b128 v1, v[2:5]
	v_mov_b32_e32 v2, s16
	v_mov_b32_e32 v3, s17
	v_mov_b32_e32 v4, s18
	v_mov_b32_e32 v5, s19
	v_mov_b32_e32 v1, s4
	s_add_i32 s4, 0, 0x23940
	ds_write_b128 v1, v[2:5]
	v_mov_b32_e32 v2, s48
	v_mov_b32_e32 v3, s49
	v_mov_b32_e32 v4, s50
	v_mov_b32_e32 v5, s51
	v_mov_b32_e32 v1, s4
	s_add_i32 s4, 0, 0x23950
	ds_write_b128 v1, v[2:5]
	v_mov_b32_e32 v2, s52
	v_mov_b32_e32 v3, s53
	v_mov_b32_e32 v4, s54
	v_mov_b32_e32 v5, s55
	v_mov_b32_e32 v1, s4
	s_add_i32 s4, 0, 0x23960
	ds_write_b128 v1, v[2:5]
	v_mov_b32_e32 v1, s4
	s_load_dwordx16 s[4:19], s[0:1], 0x80
	v_mov_b32_e32 v2, s56
	v_mov_b32_e32 v3, s57
	v_mov_b32_e32 v4, s58
	v_mov_b32_e32 v5, s59
	ds_write_b128 v1, v[2:5]
	v_mov_b32_e32 v2, s60
	v_mov_b32_e32 v3, s61
	v_mov_b32_e32 v4, s62
	v_mov_b32_e32 v5, s63
	v_mov_b32_e32 v1, s20
	ds_write_b128 v1, v[2:5]
	s_waitcnt lgkmcnt(0)
	v_mov_b32_e32 v2, s4
	s_add_i32 s4, 0, 0x23980
	v_mov_b32_e32 v3, s5
	v_mov_b32_e32 v4, s6
	v_mov_b32_e32 v5, s7
	v_mov_b32_e32 v1, s4
	s_add_i32 s4, 0, 0x23990
	ds_write_b128 v1, v[2:5]
	v_mov_b32_e32 v2, s8
	v_mov_b32_e32 v3, s9
	v_mov_b32_e32 v4, s10
	v_mov_b32_e32 v5, s11
	v_mov_b32_e32 v1, s4
	s_add_i32 s4, 0, 0x239a0
	ds_write_b128 v1, v[2:5]
	v_mov_b32_e32 v1, s4
	s_load_dwordx2 s[4:5], s[0:1], 0xc0
	v_mov_b32_e32 v2, s12
	v_mov_b32_e32 v3, s13
	v_mov_b32_e32 v4, s14
	v_mov_b32_e32 v5, s15
	s_add_i32 s6, 0, 0x239b0
	ds_write_b128 v1, v[2:5]
	v_mov_b32_e32 v2, s16
	v_mov_b32_e32 v3, s17
	v_mov_b32_e32 v4, s18
	v_mov_b32_e32 v5, s19
	v_mov_b32_e32 v1, s6
	s_add_i32 s6, 0, 0x239c0
	ds_write_b128 v1, v[2:5]
	v_mov_b32_e32 v1, s6
	s_waitcnt lgkmcnt(0)
	v_mov_b64_e32 v[2:3], s[4:5]
	ds_write_b64 v1, v[2:3]

; __device__ __forceinline__ int tidx() { int t = threadIdx.x; asm volatile("" : "+v"(t)); return t; }
; #define LAS __attribute__((address_space(3)))
; __device__ __forceinline__ void phase_prologue(const P& p, unsigned char* ws, LAS unsigned char* lds, int wg, int nwg) {
;     const int tid = tidx(), lane = tid & 63, wave = tid >> 6;
;     LAS float* scr = (LAS float*)(lds + wave * 16384);
;     const int gw = wg * NWAVES + wave, NGW = nwg * NWAVES;
;     constexpr int I_IN = (D / 64) * (NZ / 32), I_UH = (HW / 64) * (D / 32), I_UG = I_UH, I_OUT = (D / 64) * (D / 32), I_F1 = (D / 64) * (DFF / 32), I_F2 = (DFF / 64) * (D / 32), I_PL = (PLE / 64) * (D / 32), I_PG = I_OUT;
;     constexpr int I_LAYER = I_IN + I_UH + I_UG + I_OUT + I_F1 + I_F2 + I_PL + I_PG;
;     for (int it = gw; it < DEPTH * I_LAYER; it += NGW) {
.Lcv_entry:
	v_readlane_b32 s18, v249, 4
	s_mov_b32 s26, s2
	s_mov_b32 s24, s95
	v_readlane_b32 s19, v249, 5
	v_readlane_b32 s0, v250, 0
	s_bitcmp1_b32 s0, 0
	s_cbranch_scc0 .Lcv_m0
	v_readlane_b32 s26, v250, 4
	v_readlane_b32 s24, v250, 5

; __device__ __forceinline__ void phase_prologue(const P& p, unsigned char* ws, LAS unsigned char* lds, int wg, int nwg) {
;     ...
;     for (int it = gw; it < DEPTH * I_LAYER; it += NGW) {
;         const int l = it / I_LAYER; int r = it % I_LAYER;
;         if (r < I_IN) { const int nb = r % (NZ / 32), kb = r / (NZ / 32), n0 = nb * 32; bf16_t* WT = (bf16_t*)(ws + WS_WIN) + (size_t)l * NZ * D; const float* Win = p.w_in + (size_t)l * D * NIN; const float* kg = p.n_pre_mix + l * D;
;             if (n0 >= 7168 && n0 < 7680) fold_item(Win, p.wgg + (size_t)l * GR * GKW, kg, WT, kb * 64, n0 - 7168, n0, scr, lane);
;             else { const int ns = n0 < 7168 ? n0 : n0 - 496; const float sc = (n0 >= 4096 && n0 < 4608) ? 0.08838834764831845f : 1.f; transpose_item(Win, NIN, kg, sc, WT, D, kb * 64, ns, n0, scr, lane); }
;             continue; } r -= I_IN;
;         if (r < I_UH) { transpose_item(p.w_hup + (size_t)l * HW * D, D, nullptr, 1.f, (bf16_t*)(ws + WS_WUH) + (size_t)l * D * HW, HW, (r / (D / 32)) * 64, (r % (D / 32)) * 32, (r % (D / 32)) * 32, scr, lane); continue; } r -= I_UH;
;         if (r < I_UG) { transpose_item(p.w_gup + (size_t)l * GVW * D, D, nullptr, 1.f, (bf16_t*)(ws + WS_WUG) + (size_t)l * D * GVW, GVW, (r / (D / 32)) * 64, (r % (D / 32)) * 32, (r % (D / 32)) * 32, scr, lane); continue; } r -= I_UG;
;         if (r < I_OUT) { transpose_item(p.w_out + (size_t)l * D * D, D, nullptr, 1.f, (bf16_t*)(ws + WS_WOUT) + (size_t)l * D * D, D, (r / (D / 32)) * 64, (r % (D / 32)) * 32, (r % (D / 32)) * 32, scr, lane); continue; } r -= I_OUT;
;         if (r < I_F1) { transpose_item(p.w_ff1 + (size_t)l * D * DFF, DFF, p.n_pre_ffn + l * D, 1.f, (bf16_t*)(ws + WS_WFF1) + (size_t)l * DFF * D, D, (r / (DFF / 32)) * 64, (r % (DFF / 32)) * 32, (r % (DFF / 32)) * 32, scr, lane); continue; } r -= I_F1;
;         if (r < I_F2) { transpose_item(p.w_ff2 + (size_t)l * DFF * D, D, nullptr, 1.f, (bf16_t*)(ws + WS_WFF2) + (size_t)l * D * DFF, DFF, (r / (D / 32)) * 64, (r % (D / 32)) * 32, (r % (D / 32)) * 32, scr, lane); continue; } r -= I_F2;
;         if (r < I_PL) { transpose_item(p.w_ple + (size_t)l * PLE * D, D, nullptr, 1.f, (bf16_t*)(ws + WS_WPLE) + (size_t)l * D * PLE, PLE, (r / (D / 32)) * 64, (r % (D / 32)) * 32, (r % (D / 32)) * 32, scr, lane); continue; } r -= I_PL;
.LBB0_49:
	s_or_b64 exec, exec, s[54:55]
	v_readlane_b32 s0, v250, 0
	s_cmp_eq_u32 s0, 1
	s_cbranch_scc1 .Lcv_rett
	s_cmp_eq_u32 s0, 3
	s_cbranch_scc1 .Lcw_rett
	s_cmp_eq_u32 s0, 2
	s_cbranch_scc1 .Lcv_p0c
	s_mov_b32 s0, 0x21300
	v_writelane_b32 v250, s0, 1
	s_mov_b32 s0, 0x21c00
	v_writelane_b32 v250, s0, 2
	s_mov_b32 s0, 0x21bff
	v_writelane_b32 v250, s0, 3
	s_mov_b32 s0, 2
	v_writelane_b32 v250, s0, 0
	s_branch .Lcv_entry
.Lcv_rett:
	s_branch .Lcv_return
.Lcw_rett:
	s_branch .Lcw_return

; #define PH_END } if (ph >= lo && ph + 1 < hi) for (int rb = 0; rb < REP_BAR; ++rb) xcd_barrier(bar); ++ph;
; __device__ __forceinline__ void phase_prologue(const P& p, unsigned char* ws, LAS unsigned char* lds, int wg, int nwg) {
;     ...
;     for (int it = gw; it < DEPTH * I_LAYER; it += NGW) {
;         const int l = it / I_LAYER; int r = it % I_LAYER;
; __global__ void __launch_bounds__(NTHR, 2) mega(const Args a) {
;     ...
;         EpiA<FIn> E{f};
;         for (int rgp = 0; rgp < REP_G[1]; ++rgp) pg8::gemm_phase<EpiA<FIn>, pg8::StaticOrder, true, true>(lds, g, S, E);
;         }
;         PH_END
.LBB0_945:
	v_readlane_b32 s0, v248, 27
	s_cmp_gt_u32 s0, 2
	s_cbranch_scc1 .Lcw_skip
	v_readlane_b32 s1, v248, 19
	s_cmpk_lt_u32 s1, 0xee
	s_cbranch_scc1 .Lcw_skip
	s_waitcnt lgkmcnt(0)
	s_barrier
	v_writelane_b32 v251, s3, 0
	v_writelane_b32 v251, s4, 1
	v_writelane_b32 v251, s5, 2
	v_writelane_b32 v251, s6, 3
	v_writelane_b32 v251, s7, 4
	v_writelane_b32 v251, s8, 5
	v_writelane_b32 v251, s9, 6
	v_writelane_b32 v251, s10, 7
	v_writelane_b32 v251, s11, 8
	v_writelane_b32 v251, s12, 9
	v_writelane_b32 v251, s13, 10
	v_writelane_b32 v251, s14, 11
	v_writelane_b32 v251, s15, 12
	v_writelane_b32 v251, s16, 13
	v_writelane_b32 v251, s17, 14
	v_writelane_b32 v251, s18, 15
	v_writelane_b32 v251, s19, 16
	v_writelane_b32 v251, s20, 17
	v_writelane_b32 v251, s21, 18
	v_writelane_b32 v251, s23, 20
	v_writelane_b32 v251, s24, 21
	v_writelane_b32 v251, s25, 22
	v_writelane_b32 v251, s26, 23
	v_writelane_b32 v251, s27, 24
	v_writelane_b32 v251, s28, 25
	v_writelane_b32 v251, s29, 26
	v_writelane_b32 v251, s30, 27
	v_writelane_b32 v251, s31, 28
	v_writelane_b32 v251, s32, 29
	v_writelane_b32 v251, s33, 30
	v_writelane_b32 v251, s34, 31
	v_writelane_b32 v251, s35, 32
	v_writelane_b32 v251, s36, 33
	v_writelane_b32 v251, s37, 34
	v_writelane_b32 v251, s38, 35
	v_writelane_b32 v251, s39, 36
	v_writelane_b32 v251, s40, 37
	v_writelane_b32 v251, s41, 38
	v_writelane_b32 v251, s42, 39
	v_writelane_b32 v251, s43, 40
	v_writelane_b32 v251, s44, 41
	v_writelane_b32 v251, s45, 42
	v_writelane_b32 v251, s46, 43
	v_writelane_b32 v251, s47, 44
	v_writelane_b32 v251, s48, 45
	v_writelane_b32 v251, s49, 46
	v_writelane_b32 v251, s50, 47
	v_writelane_b32 v251, s51, 48
	v_writelane_b32 v251, s52, 49
	v_writelane_b32 v251, s53, 50
	v_writelane_b32 v251, s54, 51
	v_writelane_b32 v251, s55, 52
	v_writelane_b32 v251, s56, 53
	v_writelane_b32 v251, s57, 54
	v_writelane_b32 v251, s58, 55
	v_writelane_b32 v251, s59, 56
	v_writelane_b32 v251, s60, 57
	v_writelane_b32 v251, s61, 58
	v_writelane_b32 v251, s62, 59
	v_writelane_b32 v251, s63, 60
	v_writelane_b32 v251, s64, 61
	v_writelane_b32 v251, s65, 62
	v_writelane_b32 v251, s66, 63
	v_writelane_b32 v252, s67, 0
	v_writelane_b32 v252, s68, 1
	v_writelane_b32 v252, s69, 2
	v_writelane_b32 v252, s70, 3
	v_writelane_b32 v252, s71, 4
	v_writelane_b32 v252, s72, 5
	v_writelane_b32 v252, s73, 6
	v_writelane_b32 v252, s74, 7
	v_writelane_b32 v252, s75, 8
	v_writelane_b32 v252, s76, 9
	v_writelane_b32 v252, s77, 10
	v_writelane_b32 v252, s78, 11
	v_writelane_b32 v252, s79, 12
	v_writelane_b32 v252, s80, 13
	v_writelane_b32 v252, s81, 14
	v_writelane_b32 v252, s82, 15
	v_writelane_b32 v252, s83, 16
	v_writelane_b32 v252, s84, 17
	v_writelane_b32 v252, s85, 18
	v_writelane_b32 v252, s86, 19
	v_writelane_b32 v252, s87, 20
	v_writelane_b32 v252, s88, 21
	v_writelane_b32 v252, s89, 22
	v_writelane_b32 v252, s90, 23
	v_writelane_b32 v252, s91, 24
	v_writelane_b32 v252, s92, 25
	v_writelane_b32 v252, s93, 26
	v_writelane_b32 v252, s94, 27
	v_writelane_b32 v252, s95, 28
	v_writelane_b32 v252, s96, 29
	v_writelane_b32 v252, s97, 30
	v_writelane_b32 v252, s98, 31
	v_writelane_b32 v252, s99, 32
	v_mov_b32_e32 v253, v1
	s_sub_u32 s1, s1, 0xee
	v_writelane_b32 v250, s1, 4
	s_movk_i32 s22, 18
	v_writelane_b32 v250, s22, 5
	s_mul_i32 s22, s0, 0x6c0
	s_add_i32 s22, s22, 0x1b6c0
	v_writelane_b32 v250, s22, 1
	s_add_i32 s22, s22, 0x6c0
	v_writelane_b32 v250, s22, 2
	s_add_i32 s22, s22, -1
	v_writelane_b32 v250, s22, 3
	s_mov_b32 s22, 3
	v_writelane_b32 v250, s22, 0
	s_branch .Lcv_entry
; __device__ __forceinline__ unsigned xb_add(unsigned* p, unsigned v) { return __hip_atomic_fetch_add(p, v, __ATOMIC_RELAXED, __HIP_MEMORY_SCOPE_AGENT); }
; __device__ __forceinline__ void xcd_barrier(const XcdBarrier& b) {
;     asm volatile("s_waitcnt vmcnt(0)" ::: "memory");
;     __syncthreads();
;     if (threadIdx.x == 0) {
;         unsigned* bar = b.bar;
;         __builtin_amdgcn_s_waitcnt(0);
;         unsigned nloc = b.st[0], nx = b.st[1];
;         if (nloc == 0u) { xcd_barrier_complete(bar, b.x, nloc, nx); b.st[0] = nloc; b.st[1] = nx; }
;         const unsigned old = xb_add(&bar[XB_XSUB(b.x)], 1u);
.Lcw_return:
	v_readlane_b32 s3, v251, 0
	v_readlane_b32 s4, v251, 1
	v_readlane_b32 s5, v251, 2
	v_readlane_b32 s6, v251, 3
	v_readlane_b32 s7, v251, 4
	v_readlane_b32 s8, v251, 5
	v_readlane_b32 s9, v251, 6
	v_readlane_b32 s10, v251, 7
	v_readlane_b32 s11, v251, 8
	v_readlane_b32 s12, v251, 9
	v_readlane_b32 s13, v251, 10
	v_readlane_b32 s14, v251, 11
	v_readlane_b32 s15, v251, 12
	v_readlane_b32 s16, v251, 13
	v_readlane_b32 s17, v251, 14
	v_readlane_b32 s18, v251, 15
	v_readlane_b32 s19, v251, 16
	v_readlane_b32 s20, v251, 17
	v_readlane_b32 s21, v251, 18
	v_readlane_b32 s23, v251, 20
	v_readlane_b32 s24, v251, 21
	v_readlane_b32 s25, v251, 22
	v_readlane_b32 s26, v251, 23
	v_readlane_b32 s27, v251, 24
	v_readlane_b32 s28, v251, 25
	v_readlane_b32 s29, v251, 26
	v_readlane_b32 s30, v251, 27
	v_readlane_b32 s31, v251, 28
	v_readlane_b32 s32, v251, 29
	v_readlane_b32 s33, v251, 30
	v_readlane_b32 s34, v251, 31
	v_readlane_b32 s35, v251, 32
	v_readlane_b32 s36, v251, 33
	v_readlane_b32 s37, v251, 34
	v_readlane_b32 s38, v251, 35
	v_readlane_b32 s39, v251, 36
	v_readlane_b32 s40, v251, 37
	v_readlane_b32 s41, v251, 38
	v_readlane_b32 s42, v251, 39
	v_readlane_b32 s43, v251, 40
	v_readlane_b32 s44, v251, 41
	v_readlane_b32 s45, v251, 42
	v_readlane_b32 s46, v251, 43
	v_readlane_b32 s47, v251, 44
	v_readlane_b32 s48, v251, 45
	v_readlane_b32 s49, v251, 46
	v_readlane_b32 s50, v251, 47
	v_readlane_b32 s51, v251, 48
	v_readlane_b32 s52, v251, 49
	v_readlane_b32 s53, v251, 50
	v_readlane_b32 s54, v251, 51
	v_readlane_b32 s55, v251, 52
	v_readlane_b32 s56, v251, 53
	v_readlane_b32 s57, v251, 54
	v_readlane_b32 s58, v251, 55
	v_readlane_b32 s59, v251, 56
	v_readlane_b32 s60, v251, 57
	v_readlane_b32 s61, v251, 58
	v_readlane_b32 s62, v251, 59
	v_readlane_b32 s63, v251, 60
	v_readlane_b32 s64, v251, 61
	v_readlane_b32 s65, v251, 62
	v_readlane_b32 s66, v251, 63
	v_readlane_b32 s67, v252, 0
	v_readlane_b32 s68, v252, 1
	v_readlane_b32 s69, v252, 2
	v_readlane_b32 s70, v252, 3
	v_readlane_b32 s71, v252, 4
	v_readlane_b32 s72, v252, 5
	v_readlane_b32 s73, v252, 6
	v_readlane_b32 s74, v252, 7
	v_readlane_b32 s75, v252, 8
	v_readlane_b32 s76, v252, 9
	v_readlane_b32 s77, v252, 10
	v_readlane_b32 s78, v252, 11
	v_readlane_b32 s79, v252, 12
	v_readlane_b32 s80, v252, 13
	v_readlane_b32 s81, v252, 14
	v_readlane_b32 s82, v252, 15
	v_readlane_b32 s83, v252, 16
	v_readlane_b32 s84, v252, 17
	v_readlane_b32 s85, v252, 18
	v_readlane_b32 s86, v252, 19
	v_readlane_b32 s87, v252, 20
	v_readlane_b32 s88, v252, 21
	v_readlane_b32 s89, v252, 22
	v_readlane_b32 s90, v252, 23
	v_readlane_b32 s91, v252, 24
	v_readlane_b32 s92, v252, 25
	v_readlane_b32 s93, v252, 26
	v_readlane_b32 s94, v252, 27
	v_readlane_b32 s95, v252, 28
	v_readlane_b32 s96, v252, 29
	v_readlane_b32 s97, v252, 30
	v_readlane_b32 s98, v252, 31
	v_readlane_b32 s99, v252, 32
	v_mov_b32_e32 v1, v253
	s_mov_b32 s22, 0
	v_writelane_b32 v250, s22, 0
.Lcw_skip:
	v_readlane_b32 s0, v249, 6
	s_or_b32 s22, s62, 1
	v_readlane_b32 s1, v249, 7
	s_cmp_lt_i32 s22, s1
	s_cselect_b64 s[10:11], -1, 0
	s_and_b64 s[0:1], s[70:71], s[10:11]
	s_andn2_b64 vcc, exec, s[0:1]
	s_cbranch_vccnz .LBB0_999
	s_waitcnt vmcnt(0)
	s_waitcnt vmcnt(0)
	s_barrier
	s_mov_b64 s[0:1], exec
	v_readlane_b32 s6, v249, 2
	v_readlane_b32 s7, v249, 3
	s_and_b64 s[6:7], s[0:1], s[6:7]
	s_mov_b64 exec, s[6:7]
	s_cbranch_execz .LBB0_998
	v_readlane_b32 s6, v248, 9
	s_waitcnt vmcnt(0) expcnt(0) lgkmcnt(0)
	s_nop 0
	v_mov_b32_e32 v2, s6
	ds_read_b32 v4, v2
	v_readlane_b32 s6, v248, 10
	s_waitcnt lgkmcnt(0)
	v_cmp_ne_u32_e32 vcc, 0, v4
	v_mov_b32_e32 v2, s6
	ds_read_b32 v2, v2
	s_cbranch_vccnz .LBB0_962
	v_readlane_b32 s8, v249, 0
	v_readlane_b32 s9, v249, 1
	s_load_dwordx2 s[6:7], s[8:9], 0x4
	s_mov_b32 s15, 1
	s_waitcnt lgkmcnt(0)
	s_mul_i32 s14, s6, s95
	s_mul_i32 s14, s14, s7
	s_branch .LBB0_950

; #define LAS __attribute__((address_space(3)))
; __device__ __forceinline__ void phase_prologue(const P& p, unsigned char* ws, LAS unsigned char* lds, int wg, int nwg) {
;     ...
;     for (int it = gw; it < DEPTH * I_LAYER; it += NGW) {
;         const int l = it / I_LAYER; int r = it % I_LAYER;
; __device__ __forceinline__ void phase_rec(const P& p, unsigned char* ws, int l, LAS unsigned char* lds, int wg, int nwg) {
;     int lrank = wg, nloop = nwg, srank = wg, nstr = nwg;
;     const bool split = nwg >= 16;
;     if (split) { const int grp = wg >> 3, ngrp = (nwg + 7) >> 3, nlg = (ngrp + 1) >> 1;
;         const int full_l = nlg * 8 - ((ngrp & 1) ? (ngrp * 8 - nwg) : 0), full_s = nwg - full_l;
;         nloop = full_l; nstr = full_s; lrank = (grp >> 1) * 8 + (wg & 7); srank = (grp >> 1) * 8 + (wg & 7);
;         if (grp & 1) lrank = 1 << 30; else srank = 1 << 30; }
;     for (int rl = 0; rl < REP_LOOP; ++rl) for (int tk = lrank; tk < 128; tk += nloop) rec_loop_task(p, ws, l, lds, tk);
.LBB0_1145:
	v_readlane_b32 s0, v248, 27
	s_cmp_gt_u32 s0, 2
	s_cbranch_scc1 .Lcv_skip
	v_readlane_b32 s1, v248, 19
	s_bitcmp1_b32 s1, 3
	s_cbranch_scc0 .Lcv_skip
	s_waitcnt lgkmcnt(0)
	s_barrier
	v_writelane_b32 v251, s3, 0
	v_writelane_b32 v251, s4, 1
	v_writelane_b32 v251, s5, 2
	v_writelane_b32 v251, s6, 3
	v_writelane_b32 v251, s7, 4
	v_writelane_b32 v251, s8, 5
	v_writelane_b32 v251, s9, 6
	v_writelane_b32 v251, s10, 7
	v_writelane_b32 v251, s11, 8
	v_writelane_b32 v251, s12, 9
	v_writelane_b32 v251, s13, 10
	v_writelane_b32 v251, s14, 11
	v_writelane_b32 v251, s15, 12
	v_writelane_b32 v251, s16, 13
	v_writelane_b32 v251, s17, 14
	v_writelane_b32 v251, s18, 15
	v_writelane_b32 v251, s19, 16
	v_writelane_b32 v251, s20, 17
	v_writelane_b32 v251, s21, 18
	v_writelane_b32 v251, s23, 20
	v_writelane_b32 v251, s24, 21
	v_writelane_b32 v251, s25, 22
	v_writelane_b32 v251, s26, 23
	v_writelane_b32 v251, s27, 24
	v_writelane_b32 v251, s28, 25
	v_writelane_b32 v251, s29, 26
	v_writelane_b32 v251, s30, 27
	v_writelane_b32 v251, s31, 28
	v_writelane_b32 v251, s32, 29
	v_writelane_b32 v251, s33, 30
	v_writelane_b32 v251, s34, 31
	v_writelane_b32 v251, s35, 32
	v_writelane_b32 v251, s36, 33
	v_writelane_b32 v251, s37, 34
	v_writelane_b32 v251, s38, 35
	v_writelane_b32 v251, s39, 36
	v_writelane_b32 v251, s40, 37
	v_writelane_b32 v251, s41, 38
	v_writelane_b32 v251, s42, 39
	v_writelane_b32 v251, s43, 40
	v_writelane_b32 v251, s44, 41
	v_writelane_b32 v251, s45, 42
	v_writelane_b32 v251, s46, 43
	v_writelane_b32 v251, s47, 44
	v_writelane_b32 v251, s48, 45
	v_writelane_b32 v251, s49, 46
	v_writelane_b32 v251, s50, 47
	v_writelane_b32 v251, s51, 48
	v_writelane_b32 v251, s52, 49
	v_writelane_b32 v251, s53, 50
	v_writelane_b32 v251, s54, 51
	v_writelane_b32 v251, s55, 52
	v_writelane_b32 v251, s56, 53
	v_writelane_b32 v251, s57, 54
	v_writelane_b32 v251, s58, 55
	v_writelane_b32 v251, s59, 56
	v_writelane_b32 v251, s60, 57
	v_writelane_b32 v251, s61, 58
	v_writelane_b32 v251, s62, 59
	v_writelane_b32 v251, s63, 60
	v_writelane_b32 v251, s64, 61
	v_writelane_b32 v251, s65, 62
	v_writelane_b32 v251, s66, 63
	v_writelane_b32 v252, s67, 0
	v_writelane_b32 v252, s68, 1
	v_writelane_b32 v252, s69, 2
	v_writelane_b32 v252, s70, 3
	v_writelane_b32 v252, s71, 4
	v_writelane_b32 v252, s72, 5
	v_writelane_b32 v252, s73, 6
	v_writelane_b32 v252, s74, 7
	v_writelane_b32 v252, s75, 8
	v_writelane_b32 v252, s76, 9
	v_writelane_b32 v252, s77, 10
	v_writelane_b32 v252, s78, 11
	v_writelane_b32 v252, s79, 12
	v_writelane_b32 v252, s80, 13
	v_writelane_b32 v252, s81, 14
	v_writelane_b32 v252, s82, 15
	v_writelane_b32 v252, s83, 16
	v_writelane_b32 v252, s84, 17
	v_writelane_b32 v252, s85, 18
	v_writelane_b32 v252, s86, 19
	v_writelane_b32 v252, s87, 20
	v_writelane_b32 v252, s88, 21
	v_writelane_b32 v252, s89, 22
	v_writelane_b32 v252, s90, 23
	v_writelane_b32 v252, s91, 24
	v_writelane_b32 v252, s92, 25
	v_writelane_b32 v252, s93, 26
	v_writelane_b32 v252, s94, 27
	v_writelane_b32 v252, s95, 28
	v_writelane_b32 v252, s96, 29
	v_writelane_b32 v252, s97, 30
	v_writelane_b32 v252, s98, 31
	v_writelane_b32 v252, s99, 32
	v_mov_b32_e32 v253, v1
	s_lshr_b32 s22, s1, 4
	s_lshl_b32 s22, s22, 3
	s_and_b32 s1, s1, 7
	s_or_b32 s1, s22, s1
	v_writelane_b32 v250, s1, 4
	s_movk_i32 s22, 0x80
	v_writelane_b32 v250, s22, 5
	s_mul_i32 s22, s0, 0x1800
	s_add_i32 s22, s22, 0x1cb00
	v_writelane_b32 v250, s22, 1
	s_add_i32 s22, s22, 0x1800
	v_writelane_b32 v250, s22, 2
	s_add_i32 s22, s22, -1
	v_writelane_b32 v250, s22, 3
	s_mov_b32 s22, 1
	v_writelane_b32 v250, s22, 0
	s_branch .Lcv_entry
